# ab_rows (a/b gate columns) de-serialised: gate weights staged once in LDS, all 32 activation loads issued up front with counted vmcnt/lgkmcnt waits, ss2 fetched as one dwordx4; on top of silu hoist
# speedup vs baseline: 1.0107x; 1.0036x over previous
.LBB0_161:
	s_cmp_gt_i32 s70, 3
	s_cselect_b64 s[0:1], -1, 0
	s_cmp_lt_i32 s71, 4
	s_cselect_b64 s[2:3], -1, 0
	s_or_b64 s[0:1], s[0:1], s[2:3]
	s_and_b64 vcc, exec, s[0:1]
	s_cbranch_vccnz .LBB0_292
	v_and_b32_e32 v22, 0x3ff, v0
	v_lshlrev_b32_e32 v23, 4, v22
	s_add_u32 s0, s68, 0x1ea00000
	s_addc_u32 s1, s69, 0
	v_add_u32_e32 v32, 0x2000, v23
	v_add_u32_e32 v34, 0x4000, v23
	v_add_u32_e32 v35, 0x6000, v23
	global_load_dwordx4 v[24:27], v23, s[0:1]
	global_load_dwordx4 v[28:31], v32, s[0:1]
	global_load_dwordx4 v[36:39], v34, s[0:1]
	global_load_dwordx4 v[40:43], v35, s[0:1]
	v_lshrrev_b32_e32 v33, 7, v22
	v_and_b32_e32 v44, 0x7f, v22
	v_mul_u32_u24_e32 v33, 0x810, v33
	v_lshl_add_u32 v33, v44, 4, v33
	s_waitcnt vmcnt(3)
	ds_write_b128 v33, v[24:27]
	s_waitcnt vmcnt(2)
	ds_write_b128 v33, v[28:31] offset:8256
	s_waitcnt vmcnt(1)
	ds_write_b128 v33, v[36:39] offset:16512
	s_waitcnt vmcnt(0)
	ds_write_b128 v33, v[40:43] offset:24768
	s_waitcnt lgkmcnt(0)
	s_barrier
	v_bfe_u32 v2, v0, 6, 4
	v_and_b32_e32 v18, 15, v0
	s_waitcnt lgkmcnt(0)
	s_add_u32 s4, s68, 0x1ea28000
	v_lshl_or_b32 v19, s10, 3, v2
	s_movk_i32 s0, 0x800
	v_and_b32_e32 v1, 0x3ff, v0
	s_addc_u32 s5, s69, 0
	v_cmp_gt_i32_e32 vcc, s0, v19
	v_lshlrev_b32_e32 v6, 2, v18
	s_and_saveexec_b64 s[6:7], vcc
	s_cbranch_execz .LBB0_169
	v_mov_b32_e32 v7, 0
	v_bfe_u32 v3, v1, 4, 2
	v_lshl_add_u64 v[4:5], s[68:69], 0, v[6:7]
	s_mov_b64 s[0:1], 0x1ea68000
	v_lshl_add_u64 v[8:9], v[4:5], 0, s[0:1]
	v_lshlrev_b32_e32 v4, 4, v3
	v_lshlrev_b32_e32 v2, 4, v2
	v_mov_b32_e32 v5, v7
	v_lshl_or_b32 v10, v18, 11, v4
	v_mov_b32_e32 v11, v7
	v_lshl_add_u32 v2, s10, 7, v2
	v_cmp_gt_u32_e64 s[2:3], 8, v18
	v_lshlrev_b32_e32 v20, 2, v3
	s_lshl_b32 s0, s11, 3
	v_lshl_add_u64 v[10:11], s[68:69], 0, v[10:11]
	v_lshl_add_u64 v[12:13], s[68:69], 0, v[4:5]
	v_or_b32_e32 v14, v2, v18
	s_lshl_b32 s1, s11, 7
	s_mov_b64 s[8:9], 0
	v_mov_b32_e32 v21, 0x358637bd
	s_mov_b32 s14, 0x800000
	s_movk_i32 s15, 0x7ff
	s_branch .LBB0_165

.LBB0_165:
	v_ashrrev_i32_e32 v15, 31, v14
	v_lshlrev_b64 v[2:3], 11, v[14:15]
	v_lshl_add_u64 v[16:17], v[12:13], 0, v[2:3]
	v_lshl_or_b32 v152, v19, 4, v20
	v_ashrrev_i32_e32 v153, 31, v152
	v_lshl_add_u64 v[154:155], v[152:153], 2, s[4:5]
	global_load_dwordx4 v[22:25], v[16:17], off
	global_load_dwordx4 v[26:29], v[16:17], off offset:64
	global_load_dwordx4 v[30:33], v[16:17], off offset:128
	global_load_dwordx4 v[34:37], v[16:17], off offset:192
	global_load_dwordx4 v[38:41], v[16:17], off offset:256
	global_load_dwordx4 v[42:45], v[16:17], off offset:320
	global_load_dwordx4 v[46:49], v[16:17], off offset:384
	global_load_dwordx4 v[50:53], v[16:17], off offset:448
	global_load_dwordx4 v[54:57], v[16:17], off offset:512
	global_load_dwordx4 v[58:61], v[16:17], off offset:576
	global_load_dwordx4 v[62:65], v[16:17], off offset:640
	global_load_dwordx4 v[66:69], v[16:17], off offset:704
	global_load_dwordx4 v[70:73], v[16:17], off offset:768
	global_load_dwordx4 v[74:77], v[16:17], off offset:832
	global_load_dwordx4 v[78:81], v[16:17], off offset:896
	global_load_dwordx4 v[82:85], v[16:17], off offset:960
	global_load_dwordx4 v[86:89], v[16:17], off offset:1024
	global_load_dwordx4 v[90:93], v[16:17], off offset:1088
	global_load_dwordx4 v[94:97], v[16:17], off offset:1152
	global_load_dwordx4 v[98:101], v[16:17], off offset:1216
	global_load_dwordx4 v[102:105], v[16:17], off offset:1280
	global_load_dwordx4 v[106:109], v[16:17], off offset:1344
	global_load_dwordx4 v[110:113], v[16:17], off offset:1408
	global_load_dwordx4 v[114:117], v[16:17], off offset:1472
	global_load_dwordx4 v[118:121], v[16:17], off offset:1536
	global_load_dwordx4 v[122:125], v[16:17], off offset:1600
	global_load_dwordx4 v[126:129], v[16:17], off offset:1664
	global_load_dwordx4 v[130:133], v[16:17], off offset:1728
	global_load_dwordx4 v[134:137], v[16:17], off offset:1792
	global_load_dwordx4 v[138:141], v[16:17], off offset:1856
	global_load_dwordx4 v[142:145], v[16:17], off offset:1920
	global_load_dwordx4 v[146:149], v[16:17], off offset:1984
	v_mul_u32_u24_e32 v150, 0x810, v18
	v_lshl_add_u32 v150, v20, 2, v150
	v_mov_b32_e32 v2, 0
	v_mov_b32_e32 v3, 0
	v_mov_b32_e32 v4, 0
	v_mov_b32_e32 v5, 0
	ds_read_b128 v[160:163], v150
	ds_read_b128 v[164:167], v150 offset:64
	ds_read_b128 v[168:171], v150 offset:128
	ds_read_b128 v[172:175], v150 offset:192
	s_waitcnt vmcnt(31) lgkmcnt(3)
	v_mfma_f32_16x16x32_bf16 v[2:5], v[22:25], v[160:163], v[2:5]
	ds_read_b128 v[176:179], v150 offset:256
	s_waitcnt vmcnt(30) lgkmcnt(3)
	v_mfma_f32_16x16x32_bf16 v[2:5], v[26:29], v[164:167], v[2:5]
	ds_read_b128 v[180:183], v150 offset:320
	s_waitcnt vmcnt(29) lgkmcnt(3)
	v_mfma_f32_16x16x32_bf16 v[2:5], v[30:33], v[168:171], v[2:5]
	ds_read_b128 v[184:187], v150 offset:384
	s_waitcnt vmcnt(28) lgkmcnt(3)
	v_mfma_f32_16x16x32_bf16 v[2:5], v[34:37], v[172:175], v[2:5]
	ds_read_b128 v[188:191], v150 offset:448
	s_waitcnt vmcnt(27) lgkmcnt(3)
	v_mfma_f32_16x16x32_bf16 v[2:5], v[38:41], v[176:179], v[2:5]
	ds_read_b128 v[160:163], v150 offset:512
	s_waitcnt vmcnt(26) lgkmcnt(3)
	v_mfma_f32_16x16x32_bf16 v[2:5], v[42:45], v[180:183], v[2:5]
	ds_read_b128 v[164:167], v150 offset:576
	s_waitcnt vmcnt(25) lgkmcnt(3)
	v_mfma_f32_16x16x32_bf16 v[2:5], v[46:49], v[184:187], v[2:5]
	ds_read_b128 v[168:171], v150 offset:640
	s_waitcnt vmcnt(24) lgkmcnt(3)
	v_mfma_f32_16x16x32_bf16 v[2:5], v[50:53], v[188:191], v[2:5]
	ds_read_b128 v[172:175], v150 offset:704
	s_waitcnt vmcnt(23) lgkmcnt(3)
	v_mfma_f32_16x16x32_bf16 v[2:5], v[54:57], v[160:163], v[2:5]
	ds_read_b128 v[176:179], v150 offset:768
	s_waitcnt vmcnt(22) lgkmcnt(3)
	v_mfma_f32_16x16x32_bf16 v[2:5], v[58:61], v[164:167], v[2:5]
	ds_read_b128 v[180:183], v150 offset:832
	s_waitcnt vmcnt(21) lgkmcnt(3)
	v_mfma_f32_16x16x32_bf16 v[2:5], v[62:65], v[168:171], v[2:5]
	ds_read_b128 v[184:187], v150 offset:896
	s_waitcnt vmcnt(20) lgkmcnt(3)
	v_mfma_f32_16x16x32_bf16 v[2:5], v[66:69], v[172:175], v[2:5]
	ds_read_b128 v[188:191], v150 offset:960
	s_waitcnt vmcnt(19) lgkmcnt(3)
	v_mfma_f32_16x16x32_bf16 v[2:5], v[70:73], v[176:179], v[2:5]
	ds_read_b128 v[160:163], v150 offset:1024
	s_waitcnt vmcnt(18) lgkmcnt(3)
	v_mfma_f32_16x16x32_bf16 v[2:5], v[74:77], v[180:183], v[2:5]
	ds_read_b128 v[164:167], v150 offset:1088
	s_waitcnt vmcnt(17) lgkmcnt(3)
	v_mfma_f32_16x16x32_bf16 v[2:5], v[78:81], v[184:187], v[2:5]
	ds_read_b128 v[168:171], v150 offset:1152
	s_waitcnt vmcnt(16) lgkmcnt(3)
	v_mfma_f32_16x16x32_bf16 v[2:5], v[82:85], v[188:191], v[2:5]
	ds_read_b128 v[172:175], v150 offset:1216
	s_waitcnt vmcnt(15) lgkmcnt(3)
	v_mfma_f32_16x16x32_bf16 v[2:5], v[86:89], v[160:163], v[2:5]
	ds_read_b128 v[176:179], v150 offset:1280
	s_waitcnt vmcnt(14) lgkmcnt(3)
	v_mfma_f32_16x16x32_bf16 v[2:5], v[90:93], v[164:167], v[2:5]
	ds_read_b128 v[180:183], v150 offset:1344
	s_waitcnt vmcnt(13) lgkmcnt(3)
	v_mfma_f32_16x16x32_bf16 v[2:5], v[94:97], v[168:171], v[2:5]
	ds_read_b128 v[184:187], v150 offset:1408
	s_waitcnt vmcnt(12) lgkmcnt(3)
	v_mfma_f32_16x16x32_bf16 v[2:5], v[98:101], v[172:175], v[2:5]
	ds_read_b128 v[188:191], v150 offset:1472
	s_waitcnt vmcnt(11) lgkmcnt(3)
	v_mfma_f32_16x16x32_bf16 v[2:5], v[102:105], v[176:179], v[2:5]
	ds_read_b128 v[160:163], v150 offset:1536
	s_waitcnt vmcnt(10) lgkmcnt(3)
	v_mfma_f32_16x16x32_bf16 v[2:5], v[106:109], v[180:183], v[2:5]
	ds_read_b128 v[164:167], v150 offset:1600
	s_waitcnt vmcnt(9) lgkmcnt(3)
	v_mfma_f32_16x16x32_bf16 v[2:5], v[110:113], v[184:187], v[2:5]
	ds_read_b128 v[168:171], v150 offset:1664
	s_waitcnt vmcnt(8) lgkmcnt(3)
	v_mfma_f32_16x16x32_bf16 v[2:5], v[114:117], v[188:191], v[2:5]
	ds_read_b128 v[172:175], v150 offset:1728
	s_waitcnt vmcnt(7) lgkmcnt(3)
	v_mfma_f32_16x16x32_bf16 v[2:5], v[118:121], v[160:163], v[2:5]
	ds_read_b128 v[176:179], v150 offset:1792
	s_waitcnt vmcnt(6) lgkmcnt(3)
	v_mfma_f32_16x16x32_bf16 v[2:5], v[122:125], v[164:167], v[2:5]
	ds_read_b128 v[180:183], v150 offset:1856
	s_waitcnt vmcnt(5) lgkmcnt(3)
	v_mfma_f32_16x16x32_bf16 v[2:5], v[126:129], v[168:171], v[2:5]
	ds_read_b128 v[184:187], v150 offset:1920
	s_waitcnt vmcnt(4) lgkmcnt(3)
	v_mfma_f32_16x16x32_bf16 v[2:5], v[130:133], v[172:175], v[2:5]
	ds_read_b128 v[188:191], v150 offset:1984
	s_waitcnt vmcnt(3) lgkmcnt(3)
	v_mfma_f32_16x16x32_bf16 v[2:5], v[134:137], v[176:179], v[2:5]
	s_waitcnt vmcnt(2) lgkmcnt(2)
	v_mfma_f32_16x16x32_bf16 v[2:5], v[138:141], v[180:183], v[2:5]
	s_waitcnt vmcnt(1) lgkmcnt(1)
	v_mfma_f32_16x16x32_bf16 v[2:5], v[142:145], v[184:187], v[2:5]
	s_waitcnt vmcnt(0) lgkmcnt(0)
	v_mfma_f32_16x16x32_bf16 v[2:5], v[146:149], v[188:191], v[2:5]
	global_load_dwordx4 v[156:159], v[154:155], off
	v_lshlrev_b64 v[192:193], 5, v[152:153]
	v_lshl_add_u64 v[192:193], v[8:9], 0, v[192:193]
	s_nop 7
	s_nop 1
	s_and_saveexec_b64 s[12:13], s[2:3]
	s_cbranch_execz .LBB0_164
	s_waitcnt vmcnt(0)
	v_fmamk_f32 v15, v156, 0x3a800000, v21
	v_mul_f32_e32 v17, 0x4b800000, v15
	v_cmp_gt_f32_e32 vcc, s14, v15
	s_nop 1
	v_cndmask_b32_e32 v15, v15, v17, vcc
	v_rsq_f32_e32 v15, v15
	s_nop 0
	v_mul_f32_e32 v17, 0x45800000, v15
	v_cndmask_b32_e32 v15, v15, v17, vcc
	v_mul_f32_e32 v2, v2, v15
	global_store_dword v[192:193], v2, off
	v_fmamk_f32 v15, v157, 0x3a800000, v21
	v_mul_f32_e32 v17, 0x4b800000, v15
	v_cmp_gt_f32_e32 vcc, s14, v15
	s_nop 1
	v_cndmask_b32_e32 v15, v15, v17, vcc
	v_rsq_f32_e32 v15, v15
	s_nop 0
	v_mul_f32_e32 v17, 0x45800000, v15
	v_cndmask_b32_e32 v15, v15, v17, vcc
	v_mul_f32_e32 v3, v3, v15
	global_store_dword v[192:193], v3, off offset:32
	v_fmamk_f32 v15, v158, 0x3a800000, v21
	v_mul_f32_e32 v17, 0x4b800000, v15
	v_cmp_gt_f32_e32 vcc, s14, v15
	s_nop 1
	v_cndmask_b32_e32 v15, v15, v17, vcc
	v_rsq_f32_e32 v15, v15
	s_nop 0
	v_mul_f32_e32 v17, 0x45800000, v15
	v_cndmask_b32_e32 v15, v15, v17, vcc
	v_mul_f32_e32 v4, v4, v15
	global_store_dword v[192:193], v4, off offset:64
	v_fmamk_f32 v15, v159, 0x3a800000, v21
	v_mul_f32_e32 v17, 0x4b800000, v15
	v_cmp_gt_f32_e32 vcc, s14, v15
	s_nop 1
	v_cndmask_b32_e32 v15, v15, v17, vcc
	v_rsq_f32_e32 v15, v15
	s_nop 0
	v_mul_f32_e32 v17, 0x45800000, v15
	v_cndmask_b32_e32 v15, v15, v17, vcc
	v_mul_f32_e32 v5, v5, v15
	global_store_dword v[192:193], v5, off offset:96
	s_branch .LBB0_164
